# stack11 with sc1 only on the gate/up epilogue (ACT) stores, tail w_down conversion stores back to plain (their acks were inside the spare workgroups serialised item loop)
# baseline (speedup 1.0000x reference)
.LBB0_150:
	s_ashr_i32 s4, s8, 31
	s_lshr_b32 s4, s4, 26
	s_add_i32 s4, s8, s4
	s_lshl_b32 s5, s4, 5
	s_and_b32 s6, s4, 0xffffffc0
	s_and_b32 s4, s5, 0xfffff800
	v_or_b32_e32 v24, s6, v6
	s_sub_i32 s4, s10, s4
	v_or_b32_e32 v26, 8, v24
	v_or_b32_e32 v28, 16, v24
	v_or_b32_e32 v30, 24, v24
	v_or_b32_e32 v32, 32, v24
	v_or_b32_e32 v34, 40, v24
	v_or_b32_e32 v36, 48, v24
	v_or_b32_e32 v38, 56, v24
	v_ashrrev_i32_e32 v25, 31, v24
	s_ashr_i32 s5, s4, 31
	v_ashrrev_i32_e32 v27, 31, v26
	v_ashrrev_i32_e32 v29, 31, v28
	v_ashrrev_i32_e32 v31, 31, v30
	v_ashrrev_i32_e32 v33, 31, v32
	v_ashrrev_i32_e32 v35, 31, v34
	v_ashrrev_i32_e32 v37, 31, v36
	v_ashrrev_i32_e32 v39, 31, v38
	v_lshlrev_b64 v[24:25], 13, v[24:25]
	v_lshl_add_u64 v[40:41], s[4:5], 2, v[2:3]
	v_lshlrev_b64 v[26:27], 13, v[26:27]
	v_lshlrev_b64 v[28:29], 13, v[28:29]
	v_lshlrev_b64 v[30:31], 13, v[30:31]
	v_lshlrev_b64 v[32:33], 13, v[32:33]
	v_lshlrev_b64 v[34:35], 13, v[34:35]
	v_lshlrev_b64 v[36:37], 13, v[36:37]
	v_lshlrev_b64 v[38:39], 13, v[38:39]
	v_lshl_add_u64 v[24:25], v[40:41], 0, v[24:25]
	v_lshl_add_u64 v[42:43], v[40:41], 0, v[26:27]
	v_lshl_add_u64 v[44:45], v[40:41], 0, v[28:29]
	v_lshl_add_u64 v[46:47], v[40:41], 0, v[30:31]
	v_lshl_add_u64 v[48:49], v[40:41], 0, v[32:33]
	v_lshl_add_u64 v[50:51], v[40:41], 0, v[34:35]
	v_lshl_add_u64 v[52:53], v[40:41], 0, v[36:37]
	v_lshl_add_u64 v[54:55], v[40:41], 0, v[38:39]
	global_load_dwordx4 v[24:27], v[24:25], off nt
	s_nop 0
	global_load_dwordx4 v[28:31], v[42:43], off nt
	global_load_dwordx4 v[32:35], v[44:45], off nt
	global_load_dwordx4 v[36:39], v[46:47], off nt
	s_nop 0
	global_load_dwordx4 v[40:43], v[48:49], off nt
	global_load_dwordx4 v[44:47], v[50:51], off nt
	s_nop 0
	global_load_dwordx4 v[48:51], v[52:53], off nt
	s_nop 0
	global_load_dwordx4 v[52:55], v[54:55], off nt
	s_ashr_i32 s7, s6, 31
	v_lshl_add_u64 v[56:57], s[6:7], 1, v[4:5]
	v_add_u32_e32 v64, s4, v6
	v_mad_i64_i32 v[58:59], s[4:5], v64, s12, v[56:57]
	v_add_u32_e32 v60, 8, v64
	v_mad_i64_i32 v[60:61], s[4:5], v60, s12, v[56:57]
	v_add_u32_e32 v62, 16, v64
	v_mad_i64_i32 v[62:63], s[4:5], v62, s12, v[56:57]
	s_add_i32 s8, s8, s9
	s_add_i32 s10, s10, s11
	s_cmpk_lt_i32 s8, 0x1600
	s_waitcnt vmcnt(0)
	ds_write2_b32 v9, v24, v25 offset1:1
	ds_write2_b32 v9, v26, v27 offset0:2 offset1:3
	ds_write2_b32 v10, v28, v29 offset1:1
	ds_write2_b32 v11, v30, v31 offset1:1
	ds_write2_b32 v12, v32, v33 offset1:1
	ds_write2_b32 v13, v34, v35 offset1:1
	ds_write2_b32 v14, v36, v37 offset1:1
	ds_write2_b32 v15, v38, v39 offset1:1
	ds_write2_b32 v16, v40, v41 offset1:1
	ds_write2_b32 v17, v42, v43 offset1:1
	ds_write2_b32 v18, v44, v45 offset1:1
	ds_write2_b32 v19, v46, v47 offset1:1
	ds_write2_b32 v20, v48, v49 offset1:1
	ds_write2_b32 v21, v50, v51 offset1:1
	ds_write2_b32 v22, v52, v53 offset1:1
	ds_write2_b32 v23, v54, v55 offset1:1
	s_waitcnt lgkmcnt(0)
	ds_read2_b32 v[24:25], v1 offset1:33
	s_waitcnt lgkmcnt(0)
	v_cvt_pk_bf16_f32 v24, v24, v25
	ds_read2_b32 v[26:27], v1 offset0:66 offset1:99
	s_waitcnt lgkmcnt(0)
	v_cvt_pk_bf16_f32 v25, v26, v27
	ds_read2_b32 v[26:27], v1 offset0:132 offset1:165
	s_waitcnt lgkmcnt(0)
	v_cvt_pk_bf16_f32 v26, v26, v27
	ds_read2_b32 v[28:29], v1 offset0:198 offset1:231
	s_waitcnt lgkmcnt(0)
	v_cvt_pk_bf16_f32 v27, v28, v29
	ds_read2_b32 v[28:29], v1 offset0:8 offset1:41
	global_store_dwordx4 v[58:59], v[24:27], off
	s_waitcnt lgkmcnt(0)
	s_nop 0
	v_cvt_pk_bf16_f32 v24, v28, v29
	ds_read2_b32 v[26:27], v1 offset0:74 offset1:107
	s_waitcnt lgkmcnt(0)
	v_cvt_pk_bf16_f32 v25, v26, v27
	ds_read2_b32 v[26:27], v1 offset0:140 offset1:173
	s_waitcnt lgkmcnt(0)
	v_cvt_pk_bf16_f32 v26, v26, v27
	ds_read2_b32 v[28:29], v1 offset0:206 offset1:239
	s_waitcnt lgkmcnt(0)
	v_cvt_pk_bf16_f32 v27, v28, v29
	ds_read2_b32 v[28:29], v1 offset0:16 offset1:49
	global_store_dwordx4 v[60:61], v[24:27], off
	s_waitcnt lgkmcnt(0)
	s_nop 0
	v_cvt_pk_bf16_f32 v24, v28, v29
	ds_read2_b32 v[26:27], v1 offset0:82 offset1:115
	s_waitcnt lgkmcnt(0)
	v_cvt_pk_bf16_f32 v25, v26, v27
	ds_read2_b32 v[26:27], v1 offset0:148 offset1:181
	s_waitcnt lgkmcnt(0)
	v_cvt_pk_bf16_f32 v26, v26, v27
	ds_read2_b32 v[28:29], v1 offset0:214 offset1:247
	s_waitcnt lgkmcnt(0)
	v_cvt_pk_bf16_f32 v27, v28, v29
	ds_read2_b32 v[28:29], v1 offset0:24 offset1:57
	global_store_dwordx4 v[62:63], v[24:27], off
	s_waitcnt lgkmcnt(0)
	s_nop 0
	v_cvt_pk_bf16_f32 v24, v28, v29
	ds_read2_b32 v[26:27], v1 offset0:90 offset1:123
	s_waitcnt lgkmcnt(0)
	v_cvt_pk_bf16_f32 v25, v26, v27
	ds_read2_b32 v[26:27], v1 offset0:156 offset1:189
	s_waitcnt lgkmcnt(0)
	v_cvt_pk_bf16_f32 v26, v26, v27
	v_add_u32_e32 v27, 24, v64
	v_mad_i64_i32 v[30:31], s[4:5], v27, s12, v[56:57]
	ds_read2_b32 v[28:29], v1 offset0:222 offset1:255
	s_waitcnt lgkmcnt(0)
	v_cvt_pk_bf16_f32 v27, v28, v29
	global_store_dwordx4 v[30:31], v[24:27], off
	s_waitcnt lgkmcnt(0)
	s_cbranch_scc1 .LBB0_150

.LBB0_155:
	s_ashr_i32 s4, s8, 31
	s_lshr_b32 s4, s4, 26
	s_add_i32 s4, s8, s4
	s_lshl_b32 s5, s4, 5
	s_and_b32 s6, s4, 0xffffffc0
	s_and_b32 s4, s5, 0xfffff800
	v_or_b32_e32 v22, s6, v6
	s_sub_i32 s4, s10, s4
	v_or_b32_e32 v24, 8, v22
	v_or_b32_e32 v26, 16, v22
	v_or_b32_e32 v28, 24, v22
	v_or_b32_e32 v30, 32, v22
	v_or_b32_e32 v32, 40, v22
	v_or_b32_e32 v34, 48, v22
	v_or_b32_e32 v36, 56, v22
	v_ashrrev_i32_e32 v23, 31, v22
	s_ashr_i32 s5, s4, 31
	v_ashrrev_i32_e32 v25, 31, v24
	v_ashrrev_i32_e32 v27, 31, v26
	v_ashrrev_i32_e32 v29, 31, v28
	v_ashrrev_i32_e32 v31, 31, v30
	v_ashrrev_i32_e32 v33, 31, v32
	v_ashrrev_i32_e32 v35, 31, v34
	v_ashrrev_i32_e32 v37, 31, v36
	v_lshlrev_b64 v[22:23], 13, v[22:23]
	v_lshl_add_u64 v[38:39], s[4:5], 2, v[2:3]
	v_lshlrev_b64 v[24:25], 13, v[24:25]
	v_lshlrev_b64 v[26:27], 13, v[26:27]
	v_lshlrev_b64 v[28:29], 13, v[28:29]
	v_lshlrev_b64 v[30:31], 13, v[30:31]
	v_lshlrev_b64 v[32:33], 13, v[32:33]
	v_lshlrev_b64 v[34:35], 13, v[34:35]
	v_lshlrev_b64 v[36:37], 13, v[36:37]
	v_lshl_add_u64 v[22:23], v[38:39], 0, v[22:23]
	v_lshl_add_u64 v[40:41], v[38:39], 0, v[24:25]
	v_lshl_add_u64 v[42:43], v[38:39], 0, v[26:27]
	v_lshl_add_u64 v[44:45], v[38:39], 0, v[28:29]
	v_lshl_add_u64 v[46:47], v[38:39], 0, v[30:31]
	v_lshl_add_u64 v[48:49], v[38:39], 0, v[32:33]
	v_lshl_add_u64 v[50:51], v[38:39], 0, v[34:35]
	v_lshl_add_u64 v[52:53], v[38:39], 0, v[36:37]
	global_load_dwordx4 v[22:25], v[22:23], off nt
	s_nop 0
	global_load_dwordx4 v[26:29], v[40:41], off nt
	global_load_dwordx4 v[30:33], v[42:43], off nt
	global_load_dwordx4 v[34:37], v[44:45], off nt
	s_nop 0
	global_load_dwordx4 v[38:41], v[46:47], off nt
	global_load_dwordx4 v[42:45], v[48:49], off nt
	s_nop 0
	global_load_dwordx4 v[46:49], v[50:51], off nt
	s_nop 0
	global_load_dwordx4 v[50:53], v[52:53], off nt
	s_ashr_i32 s7, s6, 31
	v_lshl_add_u64 v[54:55], s[6:7], 1, v[4:5]
	v_add_u32_e32 v62, s4, v6
	v_mad_i64_i32 v[56:57], s[4:5], v62, s12, v[54:55]
	v_add_u32_e32 v58, 8, v62
	v_mad_i64_i32 v[58:59], s[4:5], v58, s12, v[54:55]
	v_add_u32_e32 v60, 16, v62
	v_mad_i64_i32 v[60:61], s[4:5], v60, s12, v[54:55]
	s_add_i32 s8, s8, s9
	s_add_i32 s10, s10, s11
	s_cmpk_gt_i32 s8, 0x15ff
	s_waitcnt vmcnt(0)
	ds_write2_b32 v7, v22, v23 offset1:1
	ds_write2_b32 v7, v24, v25 offset0:2 offset1:3
	ds_write2_b32 v8, v26, v27 offset1:1
	ds_write2_b32 v9, v28, v29 offset1:1
	ds_write2_b32 v10, v30, v31 offset1:1
	ds_write2_b32 v11, v32, v33 offset1:1
	ds_write2_b32 v12, v34, v35 offset1:1
	ds_write2_b32 v13, v36, v37 offset1:1
	ds_write2_b32 v14, v38, v39 offset1:1
	ds_write2_b32 v15, v40, v41 offset1:1
	ds_write2_b32 v16, v42, v43 offset1:1
	ds_write2_b32 v17, v44, v45 offset1:1
	ds_write2_b32 v18, v46, v47 offset1:1
	ds_write2_b32 v19, v48, v49 offset1:1
	ds_write2_b32 v20, v50, v51 offset1:1
	ds_write2_b32 v21, v52, v53 offset1:1
	s_waitcnt lgkmcnt(0)
	ds_read2_b32 v[22:23], v1 offset1:33
	s_waitcnt lgkmcnt(0)
	v_cvt_pk_bf16_f32 v22, v22, v23
	ds_read2_b32 v[24:25], v1 offset0:66 offset1:99
	s_waitcnt lgkmcnt(0)
	v_cvt_pk_bf16_f32 v23, v24, v25
	ds_read2_b32 v[24:25], v1 offset0:132 offset1:165
	s_waitcnt lgkmcnt(0)
	v_cvt_pk_bf16_f32 v24, v24, v25
	ds_read2_b32 v[26:27], v1 offset0:198 offset1:231
	s_waitcnt lgkmcnt(0)
	v_cvt_pk_bf16_f32 v25, v26, v27
	ds_read2_b32 v[26:27], v1 offset0:8 offset1:41
	global_store_dwordx4 v[56:57], v[22:25], off
	s_waitcnt lgkmcnt(0)
	s_nop 0
	v_cvt_pk_bf16_f32 v22, v26, v27
	ds_read2_b32 v[24:25], v1 offset0:74 offset1:107
	s_waitcnt lgkmcnt(0)
	v_cvt_pk_bf16_f32 v23, v24, v25
	ds_read2_b32 v[24:25], v1 offset0:140 offset1:173
	s_waitcnt lgkmcnt(0)
	v_cvt_pk_bf16_f32 v24, v24, v25
	ds_read2_b32 v[26:27], v1 offset0:206 offset1:239
	s_waitcnt lgkmcnt(0)
	v_cvt_pk_bf16_f32 v25, v26, v27
	ds_read2_b32 v[26:27], v1 offset0:16 offset1:49
	global_store_dwordx4 v[58:59], v[22:25], off
	s_waitcnt lgkmcnt(0)
	s_nop 0
	v_cvt_pk_bf16_f32 v22, v26, v27
	ds_read2_b32 v[24:25], v1 offset0:82 offset1:115
	s_waitcnt lgkmcnt(0)
	v_cvt_pk_bf16_f32 v23, v24, v25
	ds_read2_b32 v[24:25], v1 offset0:148 offset1:181
	s_waitcnt lgkmcnt(0)
	v_cvt_pk_bf16_f32 v24, v24, v25
	ds_read2_b32 v[26:27], v1 offset0:214 offset1:247
	s_waitcnt lgkmcnt(0)
	v_cvt_pk_bf16_f32 v25, v26, v27
	ds_read2_b32 v[26:27], v1 offset0:24 offset1:57
	global_store_dwordx4 v[60:61], v[22:25], off
	s_waitcnt lgkmcnt(0)
	s_nop 0
	v_cvt_pk_bf16_f32 v22, v26, v27
	ds_read2_b32 v[24:25], v1 offset0:90 offset1:123
	s_waitcnt lgkmcnt(0)
	v_cvt_pk_bf16_f32 v23, v24, v25
	ds_read2_b32 v[24:25], v1 offset0:156 offset1:189
	s_waitcnt lgkmcnt(0)
	v_cvt_pk_bf16_f32 v24, v24, v25
	v_add_u32_e32 v25, 24, v62
	v_mad_i64_i32 v[28:29], s[4:5], v25, s12, v[54:55]
	ds_read2_b32 v[26:27], v1 offset0:222 offset1:255
	s_waitcnt lgkmcnt(0)
	v_cvt_pk_bf16_f32 v25, v26, v27
	global_store_dwordx4 v[28:29], v[22:25], off
	s_waitcnt lgkmcnt(0)
	s_cbranch_scc0 .LBB0_155

.LBB0_2483:
	s_ashr_i32 s0, s6, 31
	s_lshr_b32 s0, s0, 26
	s_add_i32 s0, s6, s0
	s_lshl_b32 s1, s0, 5
	s_and_b32 s4, s0, 0xffffffc0
	s_and_b32 s0, s1, 0xfffff800
	v_or_b32_e32 v24, s4, v6
	s_sub_i32 s0, s8, s0
	v_or_b32_e32 v26, 8, v24
	v_or_b32_e32 v28, 16, v24
	v_or_b32_e32 v30, 24, v24
	v_or_b32_e32 v32, 32, v24
	v_or_b32_e32 v34, 40, v24
	v_or_b32_e32 v36, 48, v24
	v_or_b32_e32 v38, 56, v24
	v_ashrrev_i32_e32 v25, 31, v24
	s_ashr_i32 s1, s0, 31
	v_ashrrev_i32_e32 v27, 31, v26
	v_ashrrev_i32_e32 v29, 31, v28
	v_ashrrev_i32_e32 v31, 31, v30
	v_ashrrev_i32_e32 v33, 31, v32
	v_ashrrev_i32_e32 v35, 31, v34
	v_ashrrev_i32_e32 v37, 31, v36
	v_ashrrev_i32_e32 v39, 31, v38
	v_lshlrev_b64 v[24:25], 13, v[24:25]
	v_lshl_add_u64 v[40:41], s[0:1], 2, v[2:3]
	v_lshlrev_b64 v[26:27], 13, v[26:27]
	v_lshlrev_b64 v[28:29], 13, v[28:29]
	v_lshlrev_b64 v[30:31], 13, v[30:31]
	v_lshlrev_b64 v[32:33], 13, v[32:33]
	v_lshlrev_b64 v[34:35], 13, v[34:35]
	v_lshlrev_b64 v[36:37], 13, v[36:37]
	v_lshlrev_b64 v[38:39], 13, v[38:39]
	v_lshl_add_u64 v[24:25], v[40:41], 0, v[24:25]
	v_lshl_add_u64 v[42:43], v[40:41], 0, v[26:27]
	v_lshl_add_u64 v[44:45], v[40:41], 0, v[28:29]
	v_lshl_add_u64 v[46:47], v[40:41], 0, v[30:31]
	v_lshl_add_u64 v[48:49], v[40:41], 0, v[32:33]
	v_lshl_add_u64 v[50:51], v[40:41], 0, v[34:35]
	v_lshl_add_u64 v[52:53], v[40:41], 0, v[36:37]
	v_lshl_add_u64 v[54:55], v[40:41], 0, v[38:39]
	global_load_dwordx4 v[24:27], v[24:25], off nt
	s_nop 0
	global_load_dwordx4 v[28:31], v[42:43], off nt
	global_load_dwordx4 v[32:35], v[44:45], off nt
	global_load_dwordx4 v[36:39], v[46:47], off nt
	s_nop 0
	global_load_dwordx4 v[40:43], v[48:49], off nt
	global_load_dwordx4 v[44:47], v[50:51], off nt
	s_nop 0
	global_load_dwordx4 v[48:51], v[52:53], off nt
	s_nop 0
	global_load_dwordx4 v[52:55], v[54:55], off nt
	s_ashr_i32 s5, s4, 31
	v_lshl_add_u64 v[56:57], s[4:5], 1, v[4:5]
	v_add_u32_e32 v64, s0, v6
	v_mad_i64_i32 v[58:59], s[0:1], v64, s10, v[56:57]
	v_add_u32_e32 v60, 8, v64
	v_mad_i64_i32 v[60:61], s[0:1], v60, s10, v[56:57]
	v_add_u32_e32 v62, 16, v64
	v_mad_i64_i32 v[62:63], s[0:1], v62, s10, v[56:57]
	s_add_i32 s6, s6, s7
	s_add_i32 s8, s8, s9
	s_cmpk_lt_i32 s6, 0x1600
	s_waitcnt vmcnt(0)
	ds_write2_b32 v9, v24, v25 offset1:1
	ds_write2_b32 v9, v26, v27 offset0:2 offset1:3
	ds_write2_b32 v10, v28, v29 offset1:1
	ds_write2_b32 v11, v30, v31 offset1:1
	ds_write2_b32 v12, v32, v33 offset1:1
	ds_write2_b32 v13, v34, v35 offset1:1
	ds_write2_b32 v14, v36, v37 offset1:1
	ds_write2_b32 v15, v38, v39 offset1:1
	ds_write2_b32 v16, v40, v41 offset1:1
	ds_write2_b32 v17, v42, v43 offset1:1
	ds_write2_b32 v18, v44, v45 offset1:1
	ds_write2_b32 v19, v46, v47 offset1:1
	ds_write2_b32 v20, v48, v49 offset1:1
	ds_write2_b32 v21, v50, v51 offset1:1
	ds_write2_b32 v22, v52, v53 offset1:1
	ds_write2_b32 v23, v54, v55 offset1:1
	s_waitcnt lgkmcnt(0)
	ds_read2_b32 v[24:25], v1 offset1:33
	s_waitcnt lgkmcnt(0)
	v_cvt_pk_bf16_f32 v24, v24, v25
	ds_read2_b32 v[26:27], v1 offset0:66 offset1:99
	s_waitcnt lgkmcnt(0)
	v_cvt_pk_bf16_f32 v25, v26, v27
	ds_read2_b32 v[26:27], v1 offset0:132 offset1:165
	s_waitcnt lgkmcnt(0)
	v_cvt_pk_bf16_f32 v26, v26, v27
	ds_read2_b32 v[28:29], v1 offset0:198 offset1:231
	s_waitcnt lgkmcnt(0)
	v_cvt_pk_bf16_f32 v27, v28, v29
	ds_read2_b32 v[28:29], v1 offset0:8 offset1:41
	global_store_dwordx4 v[58:59], v[24:27], off
	s_waitcnt lgkmcnt(0)
	s_nop 0
	v_cvt_pk_bf16_f32 v24, v28, v29
	ds_read2_b32 v[26:27], v1 offset0:74 offset1:107
	s_waitcnt lgkmcnt(0)
	v_cvt_pk_bf16_f32 v25, v26, v27
	ds_read2_b32 v[26:27], v1 offset0:140 offset1:173
	s_waitcnt lgkmcnt(0)
	v_cvt_pk_bf16_f32 v26, v26, v27
	ds_read2_b32 v[28:29], v1 offset0:206 offset1:239
	s_waitcnt lgkmcnt(0)
	v_cvt_pk_bf16_f32 v27, v28, v29
	ds_read2_b32 v[28:29], v1 offset0:16 offset1:49
	global_store_dwordx4 v[60:61], v[24:27], off
	s_waitcnt lgkmcnt(0)
	s_nop 0
	v_cvt_pk_bf16_f32 v24, v28, v29
	ds_read2_b32 v[26:27], v1 offset0:82 offset1:115
	s_waitcnt lgkmcnt(0)
	v_cvt_pk_bf16_f32 v25, v26, v27
	ds_read2_b32 v[26:27], v1 offset0:148 offset1:181
	s_waitcnt lgkmcnt(0)
	v_cvt_pk_bf16_f32 v26, v26, v27
	ds_read2_b32 v[28:29], v1 offset0:214 offset1:247
	s_waitcnt lgkmcnt(0)
	v_cvt_pk_bf16_f32 v27, v28, v29
	ds_read2_b32 v[28:29], v1 offset0:24 offset1:57
	global_store_dwordx4 v[62:63], v[24:27], off
	s_waitcnt lgkmcnt(0)
	s_nop 0
	v_cvt_pk_bf16_f32 v24, v28, v29
	ds_read2_b32 v[26:27], v1 offset0:90 offset1:123
	s_waitcnt lgkmcnt(0)
	v_cvt_pk_bf16_f32 v25, v26, v27
	ds_read2_b32 v[26:27], v1 offset0:156 offset1:189
	s_waitcnt lgkmcnt(0)
	v_cvt_pk_bf16_f32 v26, v26, v27
	v_add_u32_e32 v27, 24, v64
	v_mad_i64_i32 v[30:31], s[0:1], v27, s10, v[56:57]
	ds_read2_b32 v[28:29], v1 offset0:222 offset1:255
	s_waitcnt lgkmcnt(0)
	v_cvt_pk_bf16_f32 v27, v28, v29
	global_store_dwordx4 v[30:31], v[24:27], off
	s_waitcnt lgkmcnt(0)
	s_cbranch_scc1 .LBB0_2483

.LBB0_2488:
	s_ashr_i32 s0, s6, 31
	s_lshr_b32 s0, s0, 26
	s_add_i32 s0, s6, s0
	s_lshl_b32 s1, s0, 5
	s_and_b32 s4, s0, 0xffffffc0
	s_and_b32 s0, s1, 0xfffff800
	v_or_b32_e32 v22, s4, v6
	s_sub_i32 s0, s8, s0
	v_or_b32_e32 v24, 8, v22
	v_or_b32_e32 v26, 16, v22
	v_or_b32_e32 v28, 24, v22
	v_or_b32_e32 v30, 32, v22
	v_or_b32_e32 v32, 40, v22
	v_or_b32_e32 v34, 48, v22
	v_or_b32_e32 v36, 56, v22
	v_ashrrev_i32_e32 v23, 31, v22
	s_ashr_i32 s1, s0, 31
	v_ashrrev_i32_e32 v25, 31, v24
	v_ashrrev_i32_e32 v27, 31, v26
	v_ashrrev_i32_e32 v29, 31, v28
	v_ashrrev_i32_e32 v31, 31, v30
	v_ashrrev_i32_e32 v33, 31, v32
	v_ashrrev_i32_e32 v35, 31, v34
	v_ashrrev_i32_e32 v37, 31, v36
	v_lshlrev_b64 v[22:23], 13, v[22:23]
	v_lshl_add_u64 v[38:39], s[0:1], 2, v[2:3]
	v_lshlrev_b64 v[24:25], 13, v[24:25]
	v_lshlrev_b64 v[26:27], 13, v[26:27]
	v_lshlrev_b64 v[28:29], 13, v[28:29]
	v_lshlrev_b64 v[30:31], 13, v[30:31]
	v_lshlrev_b64 v[32:33], 13, v[32:33]
	v_lshlrev_b64 v[34:35], 13, v[34:35]
	v_lshlrev_b64 v[36:37], 13, v[36:37]
	v_lshl_add_u64 v[22:23], v[38:39], 0, v[22:23]
	v_lshl_add_u64 v[40:41], v[38:39], 0, v[24:25]
	v_lshl_add_u64 v[42:43], v[38:39], 0, v[26:27]
	v_lshl_add_u64 v[44:45], v[38:39], 0, v[28:29]
	v_lshl_add_u64 v[46:47], v[38:39], 0, v[30:31]
	v_lshl_add_u64 v[48:49], v[38:39], 0, v[32:33]
	v_lshl_add_u64 v[50:51], v[38:39], 0, v[34:35]
	v_lshl_add_u64 v[52:53], v[38:39], 0, v[36:37]
	global_load_dwordx4 v[22:25], v[22:23], off nt
	s_nop 0
	global_load_dwordx4 v[26:29], v[40:41], off nt
	global_load_dwordx4 v[30:33], v[42:43], off nt
	global_load_dwordx4 v[34:37], v[44:45], off nt
	s_nop 0
	global_load_dwordx4 v[38:41], v[46:47], off nt
	global_load_dwordx4 v[42:45], v[48:49], off nt
	s_nop 0
	global_load_dwordx4 v[46:49], v[50:51], off nt
	s_nop 0
	global_load_dwordx4 v[50:53], v[52:53], off nt
	s_ashr_i32 s5, s4, 31
	v_lshl_add_u64 v[54:55], s[4:5], 1, v[4:5]
	v_add_u32_e32 v62, s0, v6
	v_mad_i64_i32 v[56:57], s[0:1], v62, s10, v[54:55]
	v_add_u32_e32 v58, 8, v62
	v_mad_i64_i32 v[58:59], s[0:1], v58, s10, v[54:55]
	v_add_u32_e32 v60, 16, v62
	v_mad_i64_i32 v[60:61], s[0:1], v60, s10, v[54:55]
	s_add_i32 s6, s6, s7
	s_add_i32 s8, s8, s9
	s_cmpk_gt_i32 s6, 0x15ff
	s_waitcnt vmcnt(0)
	ds_write2_b32 v7, v22, v23 offset1:1
	ds_write2_b32 v7, v24, v25 offset0:2 offset1:3
	ds_write2_b32 v8, v26, v27 offset1:1
	ds_write2_b32 v9, v28, v29 offset1:1
	ds_write2_b32 v10, v30, v31 offset1:1
	ds_write2_b32 v11, v32, v33 offset1:1
	ds_write2_b32 v12, v34, v35 offset1:1
	ds_write2_b32 v13, v36, v37 offset1:1
	ds_write2_b32 v14, v38, v39 offset1:1
	ds_write2_b32 v15, v40, v41 offset1:1
	ds_write2_b32 v16, v42, v43 offset1:1
	ds_write2_b32 v17, v44, v45 offset1:1
	ds_write2_b32 v18, v46, v47 offset1:1
	ds_write2_b32 v19, v48, v49 offset1:1
	ds_write2_b32 v20, v50, v51 offset1:1
	ds_write2_b32 v21, v52, v53 offset1:1
	s_waitcnt lgkmcnt(0)
	ds_read2_b32 v[22:23], v1 offset1:33
	s_waitcnt lgkmcnt(0)
	v_cvt_pk_bf16_f32 v22, v22, v23
	ds_read2_b32 v[24:25], v1 offset0:66 offset1:99
	s_waitcnt lgkmcnt(0)
	v_cvt_pk_bf16_f32 v23, v24, v25
	ds_read2_b32 v[24:25], v1 offset0:132 offset1:165
	s_waitcnt lgkmcnt(0)
	v_cvt_pk_bf16_f32 v24, v24, v25
	ds_read2_b32 v[26:27], v1 offset0:198 offset1:231
	s_waitcnt lgkmcnt(0)
	v_cvt_pk_bf16_f32 v25, v26, v27
	ds_read2_b32 v[26:27], v1 offset0:8 offset1:41
	global_store_dwordx4 v[56:57], v[22:25], off
	s_waitcnt lgkmcnt(0)
	s_nop 0
	v_cvt_pk_bf16_f32 v22, v26, v27
	ds_read2_b32 v[24:25], v1 offset0:74 offset1:107
	s_waitcnt lgkmcnt(0)
	v_cvt_pk_bf16_f32 v23, v24, v25
	ds_read2_b32 v[24:25], v1 offset0:140 offset1:173
	s_waitcnt lgkmcnt(0)
	v_cvt_pk_bf16_f32 v24, v24, v25
	ds_read2_b32 v[26:27], v1 offset0:206 offset1:239
	s_waitcnt lgkmcnt(0)
	v_cvt_pk_bf16_f32 v25, v26, v27
	ds_read2_b32 v[26:27], v1 offset0:16 offset1:49
	global_store_dwordx4 v[58:59], v[22:25], off
	s_waitcnt lgkmcnt(0)
	s_nop 0
	v_cvt_pk_bf16_f32 v22, v26, v27
	ds_read2_b32 v[24:25], v1 offset0:82 offset1:115
	s_waitcnt lgkmcnt(0)
	v_cvt_pk_bf16_f32 v23, v24, v25
	ds_read2_b32 v[24:25], v1 offset0:148 offset1:181
	s_waitcnt lgkmcnt(0)
	v_cvt_pk_bf16_f32 v24, v24, v25
	ds_read2_b32 v[26:27], v1 offset0:214 offset1:247
	s_waitcnt lgkmcnt(0)
	v_cvt_pk_bf16_f32 v25, v26, v27
	ds_read2_b32 v[26:27], v1 offset0:24 offset1:57
	global_store_dwordx4 v[60:61], v[22:25], off
	s_waitcnt lgkmcnt(0)
	s_nop 0
	v_cvt_pk_bf16_f32 v22, v26, v27
	ds_read2_b32 v[24:25], v1 offset0:90 offset1:123
	s_waitcnt lgkmcnt(0)
	v_cvt_pk_bf16_f32 v23, v24, v25
	ds_read2_b32 v[24:25], v1 offset0:156 offset1:189
	s_waitcnt lgkmcnt(0)
	v_cvt_pk_bf16_f32 v24, v24, v25
	v_add_u32_e32 v25, 24, v62
	v_mad_i64_i32 v[28:29], s[0:1], v25, s10, v[54:55]
	ds_read2_b32 v[26:27], v1 offset0:222 offset1:255
	s_waitcnt lgkmcnt(0)
	v_cvt_pk_bf16_f32 v25, v26, v27
	global_store_dwordx4 v[28:29], v[22:25], off
	s_waitcnt lgkmcnt(0)
	s_cbranch_scc0 .LBB0_2488

.LBB0_3400:
	s_ashr_i32 s0, s6, 31
	s_lshr_b32 s0, s0, 26
	s_add_i32 s0, s6, s0
	s_lshl_b32 s1, s0, 5
	s_and_b32 s4, s0, 0xffffffc0
	s_and_b32 s0, s1, 0xfffff800
	v_or_b32_e32 v24, s4, v6
	s_sub_i32 s0, s8, s0
	v_ashrrev_i32_e32 v25, 31, v24
	v_or_b32_e32 v26, 8, v24
	v_or_b32_e32 v28, 16, v24
	v_or_b32_e32 v30, 24, v24
	v_or_b32_e32 v32, 32, v24
	v_or_b32_e32 v34, 40, v24
	v_or_b32_e32 v36, 48, v24
	v_or_b32_e32 v38, 56, v24
	s_ashr_i32 s1, s0, 31
	v_lshlrev_b64 v[24:25], 13, v[24:25]
	v_ashrrev_i32_e32 v27, 31, v26
	v_ashrrev_i32_e32 v29, 31, v28
	v_ashrrev_i32_e32 v31, 31, v30
	v_ashrrev_i32_e32 v33, 31, v32
	v_ashrrev_i32_e32 v35, 31, v34
	v_ashrrev_i32_e32 v37, 31, v36
	v_ashrrev_i32_e32 v39, 31, v38
	v_lshl_add_u64 v[40:41], s[0:1], 2, v[2:3]
	v_lshlrev_b64 v[26:27], 13, v[26:27]
	v_lshlrev_b64 v[28:29], 13, v[28:29]
	v_lshlrev_b64 v[30:31], 13, v[30:31]
	v_lshlrev_b64 v[32:33], 13, v[32:33]
	v_lshlrev_b64 v[34:35], 13, v[34:35]
	v_lshlrev_b64 v[36:37], 13, v[36:37]
	v_lshlrev_b64 v[38:39], 13, v[38:39]
	v_lshl_add_u64 v[56:57], v[40:41], 0, v[24:25]
	v_lshl_add_u64 v[58:59], v[40:41], 0, v[26:27]
	v_lshl_add_u64 v[60:61], v[40:41], 0, v[28:29]
	v_lshl_add_u64 v[62:63], v[40:41], 0, v[30:31]
	v_lshl_add_u64 v[64:65], v[40:41], 0, v[32:33]
	v_lshl_add_u64 v[66:67], v[40:41], 0, v[34:35]
	v_lshl_add_u64 v[68:69], v[40:41], 0, v[36:37]
	v_lshl_add_u64 v[70:71], v[40:41], 0, v[38:39]
	global_load_dwordx4 v[24:27], v[56:57], off nt
	global_load_dwordx4 v[28:31], v[58:59], off nt
	global_load_dwordx4 v[32:35], v[60:61], off nt
	global_load_dwordx4 v[36:39], v[62:63], off nt
	global_load_dwordx4 v[40:43], v[64:65], off nt
	global_load_dwordx4 v[44:47], v[66:67], off nt
	global_load_dwordx4 v[48:51], v[68:69], off nt
	global_load_dwordx4 v[52:55], v[70:71], off nt
	s_ashr_i32 s5, s4, 31
	v_lshl_add_u64 v[56:57], s[4:5], 1, v[4:5]
	v_add_u32_e32 v64, s0, v6
	v_mad_i64_i32 v[58:59], s[0:1], v64, s10, v[56:57]
	v_add_u32_e32 v60, 8, v64
	v_mad_i64_i32 v[60:61], s[0:1], v60, s10, v[56:57]
	v_add_u32_e32 v62, 16, v64
	v_mad_i64_i32 v[62:63], s[0:1], v62, s10, v[56:57]
	s_add_i32 s6, s6, s7
	s_add_i32 s8, s8, s9
	s_cmpk_lt_i32 s6, 0x1600
	s_waitcnt vmcnt(0)
	ds_write2_b32 v9, v24, v25 offset1:1
	ds_write2_b32 v9, v26, v27 offset0:2 offset1:3
	ds_write2_b32 v10, v28, v29 offset1:1
	ds_write2_b32 v11, v30, v31 offset1:1
	ds_write2_b32 v12, v32, v33 offset1:1
	ds_write2_b32 v13, v34, v35 offset1:1
	ds_write2_b32 v14, v36, v37 offset1:1
	ds_write2_b32 v15, v38, v39 offset1:1
	ds_write2_b32 v16, v40, v41 offset1:1
	ds_write2_b32 v17, v42, v43 offset1:1
	ds_write2_b32 v18, v44, v45 offset1:1
	ds_write2_b32 v19, v46, v47 offset1:1
	ds_write2_b32 v20, v48, v49 offset1:1
	ds_write2_b32 v21, v50, v51 offset1:1
	ds_write2_b32 v22, v52, v53 offset1:1
	ds_write2_b32 v23, v54, v55 offset1:1
	s_waitcnt lgkmcnt(0)
	ds_read2_b32 v[24:25], v1 offset1:33
	s_waitcnt lgkmcnt(0)
	v_cvt_pk_bf16_f32 v24, v24, v25
	ds_read2_b32 v[26:27], v1 offset0:66 offset1:99
	s_waitcnt lgkmcnt(0)
	v_cvt_pk_bf16_f32 v25, v26, v27
	ds_read2_b32 v[26:27], v1 offset0:132 offset1:165
	s_waitcnt lgkmcnt(0)
	v_cvt_pk_bf16_f32 v26, v26, v27
	ds_read2_b32 v[28:29], v1 offset0:198 offset1:231
	s_waitcnt lgkmcnt(0)
	v_cvt_pk_bf16_f32 v27, v28, v29
	ds_read2_b32 v[28:29], v1 offset0:8 offset1:41
	global_store_dwordx4 v[58:59], v[24:27], off
	s_waitcnt lgkmcnt(0)
	s_nop 0
	v_cvt_pk_bf16_f32 v24, v28, v29
	ds_read2_b32 v[26:27], v1 offset0:74 offset1:107
	s_waitcnt lgkmcnt(0)
	v_cvt_pk_bf16_f32 v25, v26, v27
	ds_read2_b32 v[26:27], v1 offset0:140 offset1:173
	s_waitcnt lgkmcnt(0)
	v_cvt_pk_bf16_f32 v26, v26, v27
	ds_read2_b32 v[28:29], v1 offset0:206 offset1:239
	s_waitcnt lgkmcnt(0)
	v_cvt_pk_bf16_f32 v27, v28, v29
	ds_read2_b32 v[28:29], v1 offset0:16 offset1:49
	global_store_dwordx4 v[60:61], v[24:27], off
	s_waitcnt lgkmcnt(0)
	s_nop 0
	v_cvt_pk_bf16_f32 v24, v28, v29
	ds_read2_b32 v[26:27], v1 offset0:82 offset1:115
	s_waitcnt lgkmcnt(0)
	v_cvt_pk_bf16_f32 v25, v26, v27
	ds_read2_b32 v[26:27], v1 offset0:148 offset1:181
	s_waitcnt lgkmcnt(0)
	v_cvt_pk_bf16_f32 v26, v26, v27
	ds_read2_b32 v[28:29], v1 offset0:214 offset1:247
	s_waitcnt lgkmcnt(0)
	v_cvt_pk_bf16_f32 v27, v28, v29
	ds_read2_b32 v[28:29], v1 offset0:24 offset1:57
	global_store_dwordx4 v[62:63], v[24:27], off
	s_waitcnt lgkmcnt(0)
	s_nop 0
	v_cvt_pk_bf16_f32 v24, v28, v29
	ds_read2_b32 v[26:27], v1 offset0:90 offset1:123
	s_waitcnt lgkmcnt(0)
	v_cvt_pk_bf16_f32 v25, v26, v27
	ds_read2_b32 v[26:27], v1 offset0:156 offset1:189
	s_waitcnt lgkmcnt(0)
	v_cvt_pk_bf16_f32 v26, v26, v27
	v_add_u32_e32 v27, 24, v64
	v_mad_i64_i32 v[30:31], s[0:1], v27, s10, v[56:57]
	ds_read2_b32 v[28:29], v1 offset0:222 offset1:255
	s_waitcnt lgkmcnt(0)
	v_cvt_pk_bf16_f32 v27, v28, v29
	global_store_dwordx4 v[30:31], v[24:27], off
	s_waitcnt lgkmcnt(0)
	s_cbranch_scc1 .LBB0_3400

.LBB0_3405:
	s_ashr_i32 s0, s6, 31
	s_lshr_b32 s0, s0, 26
	s_add_i32 s0, s6, s0
	s_lshl_b32 s1, s0, 5
	s_and_b32 s4, s0, 0xffffffc0
	s_and_b32 s0, s1, 0xfffff800
	v_or_b32_e32 v22, s4, v6
	s_sub_i32 s0, s8, s0
	v_ashrrev_i32_e32 v23, 31, v22
	v_or_b32_e32 v24, 8, v22
	v_or_b32_e32 v26, 16, v22
	v_or_b32_e32 v28, 24, v22
	v_or_b32_e32 v30, 32, v22
	v_or_b32_e32 v32, 40, v22
	v_or_b32_e32 v34, 48, v22
	v_or_b32_e32 v36, 56, v22
	s_ashr_i32 s1, s0, 31
	v_lshlrev_b64 v[22:23], 13, v[22:23]
	v_ashrrev_i32_e32 v25, 31, v24
	v_ashrrev_i32_e32 v27, 31, v26
	v_ashrrev_i32_e32 v29, 31, v28
	v_ashrrev_i32_e32 v31, 31, v30
	v_ashrrev_i32_e32 v33, 31, v32
	v_ashrrev_i32_e32 v35, 31, v34
	v_ashrrev_i32_e32 v37, 31, v36
	v_lshl_add_u64 v[38:39], s[0:1], 2, v[2:3]
	v_lshlrev_b64 v[24:25], 13, v[24:25]
	v_lshlrev_b64 v[26:27], 13, v[26:27]
	v_lshlrev_b64 v[28:29], 13, v[28:29]
	v_lshlrev_b64 v[30:31], 13, v[30:31]
	v_lshlrev_b64 v[32:33], 13, v[32:33]
	v_lshlrev_b64 v[34:35], 13, v[34:35]
	v_lshlrev_b64 v[36:37], 13, v[36:37]
	v_lshl_add_u64 v[54:55], v[38:39], 0, v[22:23]
	v_lshl_add_u64 v[56:57], v[38:39], 0, v[24:25]
	v_lshl_add_u64 v[58:59], v[38:39], 0, v[26:27]
	v_lshl_add_u64 v[60:61], v[38:39], 0, v[28:29]
	v_lshl_add_u64 v[62:63], v[38:39], 0, v[30:31]
	v_lshl_add_u64 v[64:65], v[38:39], 0, v[32:33]
	v_lshl_add_u64 v[66:67], v[38:39], 0, v[34:35]
	v_lshl_add_u64 v[68:69], v[38:39], 0, v[36:37]
	global_load_dwordx4 v[22:25], v[54:55], off nt
	global_load_dwordx4 v[26:29], v[56:57], off nt
	global_load_dwordx4 v[30:33], v[58:59], off nt
	global_load_dwordx4 v[34:37], v[60:61], off nt
	global_load_dwordx4 v[38:41], v[62:63], off nt
	global_load_dwordx4 v[42:45], v[64:65], off nt
	global_load_dwordx4 v[46:49], v[66:67], off nt
	global_load_dwordx4 v[50:53], v[68:69], off nt
	s_ashr_i32 s5, s4, 31
	v_lshl_add_u64 v[54:55], s[4:5], 1, v[4:5]
	v_add_u32_e32 v62, s0, v6
	v_mad_i64_i32 v[56:57], s[0:1], v62, s9, v[54:55]
	v_add_u32_e32 v58, 8, v62
	v_mad_i64_i32 v[58:59], s[0:1], v58, s9, v[54:55]
	v_add_u32_e32 v60, 16, v62
	v_mad_i64_i32 v[60:61], s[0:1], v60, s9, v[54:55]
	s_add_i32 s6, s6, s7
	s_add_i32 s8, s8, s3
	s_cmpk_gt_i32 s6, 0x15ff
	s_waitcnt vmcnt(0)
	ds_write2_b32 v7, v22, v23 offset1:1
	ds_write2_b32 v7, v24, v25 offset0:2 offset1:3
	ds_write2_b32 v8, v26, v27 offset1:1
	ds_write2_b32 v9, v28, v29 offset1:1
	ds_write2_b32 v10, v30, v31 offset1:1
	ds_write2_b32 v11, v32, v33 offset1:1
	ds_write2_b32 v12, v34, v35 offset1:1
	ds_write2_b32 v13, v36, v37 offset1:1
	ds_write2_b32 v14, v38, v39 offset1:1
	ds_write2_b32 v15, v40, v41 offset1:1
	ds_write2_b32 v16, v42, v43 offset1:1
	ds_write2_b32 v17, v44, v45 offset1:1
	ds_write2_b32 v18, v46, v47 offset1:1
	ds_write2_b32 v19, v48, v49 offset1:1
	ds_write2_b32 v20, v50, v51 offset1:1
	ds_write2_b32 v21, v52, v53 offset1:1
	s_waitcnt lgkmcnt(0)
	ds_read2_b32 v[22:23], v1 offset1:33
	s_waitcnt lgkmcnt(0)
	v_cvt_pk_bf16_f32 v22, v22, v23
	ds_read2_b32 v[24:25], v1 offset0:66 offset1:99
	s_waitcnt lgkmcnt(0)
	v_cvt_pk_bf16_f32 v23, v24, v25
	ds_read2_b32 v[24:25], v1 offset0:132 offset1:165
	s_waitcnt lgkmcnt(0)
	v_cvt_pk_bf16_f32 v24, v24, v25
	ds_read2_b32 v[26:27], v1 offset0:198 offset1:231
	s_waitcnt lgkmcnt(0)
	v_cvt_pk_bf16_f32 v25, v26, v27
	ds_read2_b32 v[26:27], v1 offset0:8 offset1:41
	global_store_dwordx4 v[56:57], v[22:25], off
	s_waitcnt lgkmcnt(0)
	s_nop 0
	v_cvt_pk_bf16_f32 v22, v26, v27
	ds_read2_b32 v[24:25], v1 offset0:74 offset1:107
	s_waitcnt lgkmcnt(0)
	v_cvt_pk_bf16_f32 v23, v24, v25
	ds_read2_b32 v[24:25], v1 offset0:140 offset1:173
	s_waitcnt lgkmcnt(0)
	v_cvt_pk_bf16_f32 v24, v24, v25
	ds_read2_b32 v[26:27], v1 offset0:206 offset1:239
	s_waitcnt lgkmcnt(0)
	v_cvt_pk_bf16_f32 v25, v26, v27
	ds_read2_b32 v[26:27], v1 offset0:16 offset1:49
	global_store_dwordx4 v[58:59], v[22:25], off
	s_waitcnt lgkmcnt(0)
	s_nop 0
	v_cvt_pk_bf16_f32 v22, v26, v27
	ds_read2_b32 v[24:25], v1 offset0:82 offset1:115
	s_waitcnt lgkmcnt(0)
	v_cvt_pk_bf16_f32 v23, v24, v25
	ds_read2_b32 v[24:25], v1 offset0:148 offset1:181
	s_waitcnt lgkmcnt(0)
	v_cvt_pk_bf16_f32 v24, v24, v25
	ds_read2_b32 v[26:27], v1 offset0:214 offset1:247
	s_waitcnt lgkmcnt(0)
	v_cvt_pk_bf16_f32 v25, v26, v27
	ds_read2_b32 v[26:27], v1 offset0:24 offset1:57
	global_store_dwordx4 v[60:61], v[22:25], off
	s_waitcnt lgkmcnt(0)
	s_nop 0
	v_cvt_pk_bf16_f32 v22, v26, v27
	ds_read2_b32 v[24:25], v1 offset0:90 offset1:123
	s_waitcnt lgkmcnt(0)
	v_cvt_pk_bf16_f32 v23, v24, v25
	ds_read2_b32 v[24:25], v1 offset0:156 offset1:189
	s_waitcnt lgkmcnt(0)
	v_cvt_pk_bf16_f32 v24, v24, v25
	v_add_u32_e32 v25, 24, v62
	v_mad_i64_i32 v[28:29], s[0:1], v25, s9, v[54:55]
	ds_read2_b32 v[26:27], v1 offset0:222 offset1:255
	s_waitcnt lgkmcnt(0)
	v_cvt_pk_bf16_f32 v25, v26, v27
	global_store_dwordx4 v[28:29], v[22:25], off
	s_waitcnt lgkmcnt(0)
	s_cbranch_scc0 .LBB0_3405
